# attention k-loop: first four K-fragment ds_read_b128 of the next iteration issued right after the end-of-iteration barrier (before the l-sum tail / loop control / next prefetch issue) so their LDS lat
# speedup vs baseline: 1.0031x; 1.0031x over previous
.LBB0_716:
	s_or_b64 exec, exec, s[6:7]
	v_ashrrev_i32_e32 v32, 4, v3
	v_add_u32_e32 v4, v4, v32
	v_ashrrev_i32_e32 v5, 31, v4
	v_mov_b32_e32 v1, v2
	v_lshlrev_b64 v[26:27], 11, v[4:5]
	v_lshlrev_b32_e32 v6, 3, v3
	v_lshlrev_b64 v[24:25], 1, v[0:1]
	v_lshl_add_u64 v[4:5], s[74:75], 0, v[26:27]
	v_and_b32_e32 v7, 0x78, v6
	v_lshl_add_u64 v[4:5], v[4:5], 0, v[24:25]
	v_lshlrev_b32_e32 v102, 1, v7
	v_mov_b32_e32 v103, v2
	v_ashrrev_i32_e32 v34, 3, v3
	v_lshl_add_u64 v[8:9], v[4:5], 0, v[102:103]
	v_mad_i64_i32 v[4:5], s[6:7], v23, v34, 0
	v_and_b32_e32 v6, 56, v6
	v_lshl_add_u64 v[4:5], v[4:5], 1, v[20:21]
	v_lshlrev_b32_e32 v104, 1, v6
	v_mov_b32_e32 v105, v2
	s_mov_b32 s6, 0x10000
	v_lshl_add_u64 v[16:17], v[4:5], 0, v[104:105]
	global_load_dwordx4 v[4:7], v[8:9], off
	v_add_co_u32_e32 v8, vcc, s6, v8
	s_ashr_i32 s6, s8, 2
	s_waitcnt vmcnt(25)
	v_bfi_b32 v38, -16, s6, v3
	v_mov_b64_e32 v[28:29], s[16:17]
	v_and_b32_e32 v37, 7, v3
	s_movk_i32 s7, 0x88
	s_waitcnt vmcnt(24)
	v_lshlrev_b32_e32 v41, 1, v34
	v_add_u32_e32 v100, v38, v22
	v_bfe_u32 v35, v3, 4, 2
	v_mov_b32_e32 v33, v2
	v_mul_lo_u32 v39, v32, s7
	v_lshlrev_b32_e32 v32, 4, v37
	v_add_u32_e32 v22, 0x80, v41
	v_mad_i64_i32 v[28:29], s[6:7], v100, s20, v[28:29]
	v_addc_co_u32_e32 v9, vcc, 0, v9, vcc
	v_lshlrev_b32_e32 v18, 7, v23
	v_mov_b32_e32 v19, v2
	v_and_b32_e32 v36, 15, v3
	v_mov_b32_e32 v31, v2
	v_lshrrev_b32_e32 v103, 6, v23
	v_lshl_add_u64 v[20:21], v[20:21], 0, s[52:53]
	s_waitcnt vmcnt(23)
	v_lshlrev_b32_e32 v44, 3, v35
	v_lshlrev_b32_e32 v30, 4, v35
	v_mul_lo_u32 v40, v34, s23
	v_lshlrev_b32_e32 v3, 2, v35
	v_mad_i64_i32 v[34:35], s[6:7], v41, v23, v[32:33]
	v_mad_i64_i32 v[22:23], s[6:7], v22, v23, v[32:33]
	v_lshl_add_u64 v[28:29], v[28:29], 0, v[24:25]
	global_load_dwordx4 v[8:11], v[8:9], off
	s_nop 0
	global_load_dwordx4 v[12:15], v[16:17], off
	v_lshl_add_u64 v[16:17], v[16:17], 0, v[18:19]
	v_lshl_add_u64 v[106:107], v[20:21], 0, v[34:35]
	v_lshl_add_u64 v[108:109], v[20:21], 0, v[22:23]
	v_lshl_add_u64 v[20:21], v[28:29], 0, v[30:31]
	global_load_dwordx4 v[16:19], v[16:17], off
	v_mul_u32_u24_e32 v105, 0x110, v36
	v_mul_u32_u24_e32 v115, 0x90, v36
	v_mad_u32_u24 v152, v36, s24, v146
	v_mad_u32_u24 v153, v36, s24, v147
	v_mad_u32_u24 v154, v36, s24, v151
	v_lshlrev_b32_e32 v155, 1, v39
	v_lshlrev_b32_e32 v156, 1, v40
	v_lshl_or_b32 v26, v36, 4, v26
	global_load_dwordx4 v[36:39], v[20:21], off
	global_load_dwordx4 v[40:43], v[20:21], off offset:64
	global_load_dwordx4 v[48:51], v[20:21], off offset:128
	global_load_dwordx4 v[52:55], v[20:21], off offset:192
	v_add3_u32 v45, 16, v155, v102
	v_add3_u32 v46, 16, v156, v104
	v_lshl_add_u64 v[22:23], v[26:27], 0, v[24:25]
	v_mov_b32_e32 v24, 0
	s_mov_b32 s12, 1
	v_ashrrev_i32_e32 v101, 31, v100
	s_waitcnt vmcnt(26)
	v_lshl_add_u64 v[110:111], s[72:73], 0, v[22:23]
	s_barrier
	v_sub_u32_e32 v157, 0, v103
	v_mov_b32_e32 v116, 0xf149f2ca
	s_mov_b64 s[8:9], 0
	v_lshlrev_b32_e32 v158, 1, v44
	v_mov_b32_e32 v117, 0xf149f2ca
	v_mov_b32_e32 v25, v24
	v_mov_b32_e32 v26, v24
	v_mov_b32_e32 v27, v24
	v_mov_b32_e32 v56, v24
	s_waitcnt vmcnt(7)
	ds_write_b128 v45, v[4:7]
	s_waitcnt vmcnt(6)
	ds_write_b128 v45, v[8:11] offset:8704
	s_waitcnt vmcnt(5)
	ds_write_b128 v46, v[12:15] offset:17408
	s_waitcnt vmcnt(4)
	ds_write_b128 v46, v[16:19] offset:26624
	v_mov_b32_e32 v57, v24
	v_mov_b32_e32 v58, v24
	v_mov_b32_e32 v59, v24
	v_mov_b32_e32 v68, v24
	v_mov_b32_e32 v69, v24
	v_mov_b32_e32 v70, v24
	v_mov_b32_e32 v71, v24
	v_mov_b32_e32 v80, v24
	v_mov_b32_e32 v81, v24
	v_mov_b32_e32 v82, v24
	v_mov_b32_e32 v83, v24
	v_mov_b32_e32 v84, v24
	v_mov_b32_e32 v85, v24
	v_mov_b32_e32 v86, v24
	v_mov_b32_e32 v87, v24
	v_mov_b32_e32 v20, v24
	v_mov_b32_e32 v21, v24
	v_mov_b32_e32 v22, v24
	v_mov_b32_e32 v23, v24
	v_mov_b32_e32 v28, v24
	v_mov_b32_e32 v29, v24
	v_mov_b32_e32 v30, v24
	v_mov_b32_e32 v31, v24
	v_mov_b32_e32 v60, v24
	v_mov_b32_e32 v61, v24
	v_mov_b32_e32 v62, v24
	v_mov_b32_e32 v63, v24
	v_mov_b32_e32 v72, v24
	v_mov_b32_e32 v73, v24
	v_mov_b32_e32 v74, v24
	v_mov_b32_e32 v75, v24
	v_mov_b32_e32 v76, v24
	v_mov_b32_e32 v77, v24
	v_mov_b32_e32 v78, v24
	v_mov_b32_e32 v79, v24
	v_mov_b32_e32 v92, v24
	v_mov_b32_e32 v93, v24
	v_mov_b32_e32 v94, v24
	v_mov_b32_e32 v95, v24
	v_mov_b32_e32 v96, v24
	v_mov_b32_e32 v97, v24
	v_mov_b32_e32 v98, v24
	v_mov_b32_e32 v99, v24
	v_mov_b32_e32 v64, v24
	v_mov_b32_e32 v65, v24
	v_mov_b32_e32 v66, v24
	v_mov_b32_e32 v67, v24
	v_mov_b32_e32 v44, v24
	v_mov_b32_e32 v45, v24
	v_mov_b32_e32 v46, v24
	v_mov_b32_e32 v47, v24
	v_mov_b32_e32 v32, v24
	v_mov_b32_e32 v33, v24
	v_mov_b32_e32 v34, v24
	v_mov_b32_e32 v35, v24
	v_mov_b32_e32 v88, v24
	v_mov_b32_e32 v89, v24
	v_mov_b32_e32 v90, v24
	v_mov_b32_e32 v91, v24
	v_mov_b32_e32 v112, v24
	v_mov_b32_e32 v113, v24
	s_waitcnt vmcnt(0) lgkmcnt(0)
	s_barrier
	s_and_b32 s100, 1, s12
	s_cselect_b32 s100, 0, 0x8c00
	s_add_i32 s100, s100, 16
	v_add3_u32 v236, s100, v158, v105
	ds_read_b128 v[118:121], v236
	ds_read_b128 v[122:125], v236 offset:64
	ds_read_b128 v[126:129], v236 offset:4352
	ds_read_b128 v[130:133], v236 offset:4416
	s_branch .LBB0_718
.LBB0_717:
	s_or_b64 exec, exec, s[10:11]
	v_mov_b32_e32 v139, v136
	v_add_f32_e32 v136, 0, v161
	v_add_f32_e32 v136, v162, v136
	v_add_f32_e32 v136, v163, v136
	v_add_f32_e32 v136, v164, v136
	v_add_f32_e32 v136, v165, v136
	v_add_f32_e32 v141, v166, v136
	v_add_f32_e32 v136, 0, v167
	v_add_f32_e32 v136, v168, v136
	v_add_f32_e32 v136, v169, v136
	v_add_f32_e32 v136, v170, v136
	v_add_f32_e32 v136, v171, v136
	v_add_f32_e32 v140, v172, v136
	v_pk_add_f32 v[116:117], v[116:117], v[140:141]
	s_add_i32 s12, s12, 1
	v_pk_add_f32 v[116:117], v[118:119], v[116:117]
	s_mov_b64 s[6:7], 0x20000
	v_pk_add_f32 v[116:117], v[120:121], v[116:117]
	v_lshl_add_u64 v[106:107], v[106:107], 0, s[52:53]
	v_pk_add_f32 v[116:117], v[122:123], v[116:117]
	v_lshl_add_u64 v[108:109], v[108:109], 0, s[52:53]
	v_pk_add_f32 v[116:117], v[124:125], v[116:117]
	v_lshl_add_u64 v[110:111], v[110:111], 0, s[6:7]
	v_pk_add_f32 v[116:117], v[126:127], v[116:117]
	s_nop 0
	v_pk_add_f32 v[116:117], v[128:129], v[116:117]
	s_nop 0
	v_pk_add_f32 v[116:117], v[130:131], v[116:117]
	s_nop 0
	v_pk_add_f32 v[116:117], v[132:133], v[116:117]
	s_waitcnt lgkmcnt(0)
	s_barrier
	s_and_b32 s100, 1, s12
	s_cselect_b32 s100, 0, 0x8c00
	s_add_i32 s100, s100, 16
	v_add3_u32 v236, s100, v158, v105
	ds_read_b128 v[118:121], v236
	ds_read_b128 v[122:125], v236 offset:64
	ds_read_b128 v[126:129], v236 offset:4352
	ds_read_b128 v[130:133], v236 offset:4416
	v_pk_add_f32 v[116:117], v[134:135], v[116:117]
	s_nop 0
	v_pk_fma_f32 v[112:113], v[112:113], v[138:139], v[116:117]
	v_add_u32_e32 v116, s12, v157
	v_cmp_eq_u32_e32 vcc, 1, v116
	s_or_b64 s[8:9], vcc, s[8:9]
	v_mov_b32_e32 v116, v160
	v_mov_b32_e32 v117, v159
	s_andn2_b64 exec, exec, s[8:9]
	s_cbranch_execz .LBB0_621

.LBB0_720:
	s_or_b64 exec, exec, s[10:11]
	s_and_b32 s13, 1, s12
	s_cselect_b32 s10, 0, 0x8c00
	s_add_i32 s10, s10, 16
	v_add3_u32 v114, s10, v158, v105
	s_waitcnt lgkmcnt(3)
	v_mfma_f32_16x16x32_bf16 v[118:121], v[118:121], v[36:39], 0
	s_waitcnt lgkmcnt(1)
	v_mfma_f32_16x16x32_bf16 v[126:129], v[126:129], v[36:39], 0
	s_nop 0
	v_mfma_f32_16x16x32_bf16 v[118:121], v[122:125], v[40:43], v[118:121]
	ds_read_b128 v[122:125], v114 offset:8704
	s_waitcnt lgkmcnt(1)
	v_mfma_f32_16x16x32_bf16 v[126:129], v[130:133], v[40:43], v[126:129]
	ds_read_b128 v[130:133], v114 offset:8768
	ds_read_b128 v[138:141], v114 offset:13056
	ds_read_b128 v[160:163], v114 offset:13120
	s_waitcnt lgkmcnt(3)
	v_mfma_f32_16x16x32_bf16 v[122:125], v[122:125], v[36:39], 0
	s_waitcnt lgkmcnt(2)
	v_mfma_f32_16x16x32_bf16 v[130:133], v[130:133], v[40:43], v[122:125]
	s_nop 5
	v_max3_f32 v122, v118, s26, v119
	v_max3_f32 v122, v122, v120, v121
	v_max3_f32 v134, v122, v126, v127
	s_waitcnt lgkmcnt(1)
	v_mfma_f32_16x16x32_bf16 v[122:125], v[138:141], v[36:39], 0
	v_max3_f32 v134, v134, v128, v129
	v_max3_f32 v134, v134, v130, v131
	v_max3_f32 v134, v134, v132, v133
	s_waitcnt lgkmcnt(0)
	v_mfma_f32_16x16x32_bf16 v[138:141], v[160:163], v[40:43], v[122:125]
	s_nop 7
	v_max3_f32 v122, v134, v138, v139
	v_max3_f32 v122, v122, v140, v141
	v_mul_f32_e32 v134, 0x3e38aa3b, v122
	v_mul_f32_e32 v135, 0x3e38aa3b, v122
	ds_read_b128 v[122:125], v114 offset:128
	ds_read_b128 v[166:169], v114 offset:192
	ds_read_b128 v[170:173], v114 offset:4544
	s_nop 0
	v_permlane16_swap_b32_e32 v134, v135
	v_max_f32_e32 v134, v134, v135
	v_mov_b32_e32 v135, v134
	s_nop 1
	v_permlane32_swap_b32_e32 v134, v135
	s_waitcnt lgkmcnt(2)
	v_mfma_f32_16x16x32_bf16 v[122:125], v[122:125], v[48:51], 0
	v_max3_f32 v159, v117, v134, v135
	v_sub_f32_e32 v134, v117, v159
	v_cmp_gt_f32_e32 vcc, 0xc1000000, v134
	s_cmp_lg_u64 vcc, 0
	s_cselect_b32 s98, 1, 0
	s_cbranch_scc1 .Lmy_at_k0
	v_mov_b32_e32 v159, v117
	v_mov_b32_e32 v134, 0
